# NSA importance: 16 masked LDS atomics per step packed into 2 full-wave atomics
# speedup vs baseline: 1.0014x; 1.0014x over previous
.LBB0_1955:
	v_exp_f32_e32 v42, v138
	v_exp_f32_e32 v43, v141
	v_exp_f32_e32 v44, v139
	v_exp_f32_e32 v45, v140
	v_mul_f32_e32 v46, v146, v43
	v_add_f32_e32 v47, v42, v44
	v_add_f32_e32 v47, v45, v47
	v_mul_f32_e32 v48, 0.5, v46
	v_fma_f32 v47, v146, v47, v48
	s_mov_b32 s86, 0x1010101
	s_mov_b32 s87, 0x1010101
	s_nop 1
	v_add_f32_dpp v48, v48, v48 quad_perm:[1,0,3,2] row_mask:0xf bank_mask:0xf
	v_add_f32_dpp v47, v47, v47 quad_perm:[1,0,3,2] row_mask:0xf bank_mask:0xf
	s_nop 0
	v_add_f32_dpp v48, v48, v48 quad_perm:[2,3,0,1] row_mask:0xf bank_mask:0xf
	v_add_f32_dpp v47, v47, v47 quad_perm:[2,3,0,1] row_mask:0xf bank_mask:0xf
	s_nop 0
	v_add_f32_dpp v48, v48, v48 row_half_mirror row_mask:0xf bank_mask:0xf
	v_add_f32_dpp v47, v47, v47 row_half_mirror row_mask:0xf bank_mask:0xf
	v_cndmask_b32_e64 v234, v234, v47, s[86:87]
	v_cndmask_b32_e64 v235, v235, v48, s[86:87]
	s_lshl_b64 s[86:87], s[86:87], 1
	v_exp_f32_e32 v49, v54
	v_exp_f32_e32 v54, v55
	v_exp_f32_e32 v55, v57
	v_exp_f32_e32 v56, v56
	v_exp_f32_e32 v46, v58
	v_add_f32_e32 v48, v49, v54
	v_mul_f32_e32 v57, v146, v55
	v_add_f32_e32 v48, v56, v48
	v_mul_f32_e32 v58, 0.5, v57
	v_exp_f32_e32 v47, v59
	v_fma_f32 v59, v146, v48, v58
	s_nop 1
	v_add_f32_dpp v58, v58, v58 quad_perm:[1,0,3,2] row_mask:0xf bank_mask:0xf
	v_add_f32_dpp v59, v59, v59 quad_perm:[1,0,3,2] row_mask:0xf bank_mask:0xf
	s_nop 0
	v_add_f32_dpp v58, v58, v58 quad_perm:[2,3,0,1] row_mask:0xf bank_mask:0xf
	v_add_f32_dpp v59, v59, v59 quad_perm:[2,3,0,1] row_mask:0xf bank_mask:0xf
	s_nop 0
	v_add_f32_dpp v58, v58, v58 row_half_mirror row_mask:0xf bank_mask:0xf
	v_add_f32_dpp v59, v59, v59 row_half_mirror row_mask:0xf bank_mask:0xf
	v_cndmask_b32_e64 v234, v234, v59, s[86:87]
	v_cndmask_b32_e64 v235, v235, v58, s[86:87]
	s_lshl_b64 s[86:87], s[86:87], 1
	v_exp_f32_e32 v48, v52
	v_exp_f32_e32 v52, v53
	v_exp_f32_e32 v53, v60
	v_exp_f32_e32 v50, v50
	v_exp_f32_e32 v51, v51
	v_exp_f32_e32 v57, v61
	v_mul_f32_e32 v58, v146, v52
	v_add_f32_e32 v59, v46, v47
	v_add_f32_e32 v59, v48, v59
	v_mul_f32_e32 v60, 0.5, v58
	v_fma_f32 v59, v146, v59, v60
	s_nop 1
	v_add_f32_dpp v60, v60, v60 quad_perm:[1,0,3,2] row_mask:0xf bank_mask:0xf
	v_add_f32_dpp v59, v59, v59 quad_perm:[1,0,3,2] row_mask:0xf bank_mask:0xf
	s_nop 0
	v_add_f32_dpp v60, v60, v60 quad_perm:[2,3,0,1] row_mask:0xf bank_mask:0xf
	v_add_f32_dpp v59, v59, v59 quad_perm:[2,3,0,1] row_mask:0xf bank_mask:0xf
	s_nop 0
	v_add_f32_dpp v60, v60, v60 row_half_mirror row_mask:0xf bank_mask:0xf
	v_add_f32_dpp v59, v59, v59 row_half_mirror row_mask:0xf bank_mask:0xf
	v_cndmask_b32_e64 v234, v234, v59, s[86:87]
	v_cndmask_b32_e64 v235, v235, v60, s[86:87]
	s_lshl_b64 s[86:87], s[86:87], 1
	v_mul_f32_e32 v58, v146, v57
	v_add_f32_e32 v59, v50, v51
	v_add_f32_e32 v59, v53, v59
	v_mul_f32_e32 v60, 0.5, v58
	v_fma_f32 v59, v146, v59, v60
	s_nop 1
	v_add_f32_dpp v60, v60, v60 quad_perm:[1,0,3,2] row_mask:0xf bank_mask:0xf
	v_add_f32_dpp v59, v59, v59 quad_perm:[1,0,3,2] row_mask:0xf bank_mask:0xf
	s_nop 0
	v_add_f32_dpp v60, v60, v60 quad_perm:[2,3,0,1] row_mask:0xf bank_mask:0xf
	v_add_f32_dpp v59, v59, v59 quad_perm:[2,3,0,1] row_mask:0xf bank_mask:0xf
	s_nop 0
	v_add_f32_dpp v60, v60, v60 row_half_mirror row_mask:0xf bank_mask:0xf
	v_add_f32_dpp v59, v59, v59 row_half_mirror row_mask:0xf bank_mask:0xf
	v_cndmask_b32_e64 v234, v234, v59, s[86:87]
	v_cndmask_b32_e64 v235, v235, v60, s[86:87]
	s_lshl_b64 s[86:87], s[86:87], 1
	v_exp_f32_e32 v58, v142
	v_exp_f32_e32 v59, v145
	v_exp_f32_e32 v60, v143
	v_exp_f32_e32 v61, v144
	v_mul_f32_e32 v138, v146, v59
	v_add_f32_e32 v139, v58, v60
	v_add_f32_e32 v139, v61, v139
	v_mul_f32_e32 v140, 0.5, v138
	v_fma_f32 v139, v146, v139, v140
	s_nop 1
	v_add_f32_dpp v140, v140, v140 quad_perm:[1,0,3,2] row_mask:0xf bank_mask:0xf
	v_add_f32_dpp v139, v139, v139 quad_perm:[1,0,3,2] row_mask:0xf bank_mask:0xf
	s_nop 0
	v_add_f32_dpp v140, v140, v140 quad_perm:[2,3,0,1] row_mask:0xf bank_mask:0xf
	v_add_f32_dpp v139, v139, v139 quad_perm:[2,3,0,1] row_mask:0xf bank_mask:0xf
	s_nop 0
	v_add_f32_dpp v140, v140, v140 row_half_mirror row_mask:0xf bank_mask:0xf
	v_add_f32_dpp v139, v139, v139 row_half_mirror row_mask:0xf bank_mask:0xf
	v_cndmask_b32_e64 v234, v234, v139, s[86:87]
	v_cndmask_b32_e64 v235, v235, v140, s[86:87]
	s_lshl_b64 s[86:87], s[86:87], 1
	v_exp_f32_e32 v62, v62
	v_exp_f32_e32 v65, v65
	v_exp_f32_e32 v63, v63
	v_exp_f32_e32 v64, v64
	v_mul_f32_e32 v138, v146, v65
	v_add_f32_e32 v139, v62, v63
	v_add_f32_e32 v139, v64, v139
	v_mul_f32_e32 v140, 0.5, v138
	v_fma_f32 v139, v146, v139, v140
	s_nop 1
	v_add_f32_dpp v140, v140, v140 quad_perm:[1,0,3,2] row_mask:0xf bank_mask:0xf
	v_add_f32_dpp v139, v139, v139 quad_perm:[1,0,3,2] row_mask:0xf bank_mask:0xf
	s_nop 0
	v_add_f32_dpp v140, v140, v140 quad_perm:[2,3,0,1] row_mask:0xf bank_mask:0xf
	v_add_f32_dpp v139, v139, v139 quad_perm:[2,3,0,1] row_mask:0xf bank_mask:0xf
	s_nop 0
	v_add_f32_dpp v140, v140, v140 row_half_mirror row_mask:0xf bank_mask:0xf
	v_add_f32_dpp v139, v139, v139 row_half_mirror row_mask:0xf bank_mask:0xf
	v_cndmask_b32_e64 v234, v234, v139, s[86:87]
	v_cndmask_b32_e64 v235, v235, v140, s[86:87]
	s_lshl_b64 s[86:87], s[86:87], 1
	v_exp_f32_e32 v38, v38
	v_exp_f32_e32 v41, v41
	v_exp_f32_e32 v39, v39
	v_exp_f32_e32 v40, v40
	v_mul_f32_e32 v138, v146, v41
	v_add_f32_e32 v139, v38, v39
	v_add_f32_e32 v139, v40, v139
	v_mul_f32_e32 v140, 0.5, v138
	v_fma_f32 v139, v146, v139, v140
	s_nop 1
	v_add_f32_dpp v140, v140, v140 quad_perm:[1,0,3,2] row_mask:0xf bank_mask:0xf
	v_add_f32_dpp v139, v139, v139 quad_perm:[1,0,3,2] row_mask:0xf bank_mask:0xf
	s_nop 0
	v_add_f32_dpp v140, v140, v140 quad_perm:[2,3,0,1] row_mask:0xf bank_mask:0xf
	v_add_f32_dpp v139, v139, v139 quad_perm:[2,3,0,1] row_mask:0xf bank_mask:0xf
	s_nop 0
	v_add_f32_dpp v140, v140, v140 row_half_mirror row_mask:0xf bank_mask:0xf
	v_add_f32_dpp v139, v139, v139 row_half_mirror row_mask:0xf bank_mask:0xf
	v_cndmask_b32_e64 v234, v234, v139, s[86:87]
	v_cndmask_b32_e64 v235, v235, v140, s[86:87]
	s_lshl_b64 s[86:87], s[86:87], 1
	v_exp_f32_e32 v34, v34
	v_exp_f32_e32 v37, v37
	v_exp_f32_e32 v35, v35
	v_exp_f32_e32 v36, v36
	v_mul_f32_e32 v138, v146, v37
	v_add_f32_e32 v139, v34, v35
	v_add_f32_e32 v139, v36, v139
	v_mul_f32_e32 v140, 0.5, v138
	v_fma_f32 v139, v146, v139, v140
	s_nop 1
	v_add_f32_dpp v140, v140, v140 quad_perm:[1,0,3,2] row_mask:0xf bank_mask:0xf
	v_add_f32_dpp v139, v139, v139 quad_perm:[1,0,3,2] row_mask:0xf bank_mask:0xf
	s_nop 0
	v_add_f32_dpp v140, v140, v140 quad_perm:[2,3,0,1] row_mask:0xf bank_mask:0xf
	v_add_f32_dpp v139, v139, v139 quad_perm:[2,3,0,1] row_mask:0xf bank_mask:0xf
	s_nop 0
	v_add_f32_dpp v140, v140, v140 row_half_mirror row_mask:0xf bank_mask:0xf
	v_add_f32_dpp v139, v139, v139 row_half_mirror row_mask:0xf bank_mask:0xf
	v_cndmask_b32_e64 v234, v234, v139, s[86:87]
	v_cndmask_b32_e64 v235, v235, v140, s[86:87]
	s_lshl_b64 s[86:87], s[86:87], 1
	v_mbcnt_lo_u32_b32 v236, -1, 0
	v_mbcnt_hi_u32_b32 v236, -1, v236
	v_and_b32_e32 v236, 7, v236
	v_lshl_add_u32 v236, v236, 3, v147
	ds_add_f32 v236, v234
	ds_add_f32 v236, v235 offset:4
	s_branch .LBB0_1946

	.amdhsa_kernel _Z15yoco_megakernel5KArgsii
		.amdhsa_group_segment_fixed_size 73744
		.amdhsa_private_segment_fixed_size 0
		.amdhsa_kernarg_size 512
		.amdhsa_user_sgpr_count 2
		.amdhsa_user_sgpr_dispatch_ptr 0
		.amdhsa_user_sgpr_queue_ptr 0
		.amdhsa_user_sgpr_kernarg_segment_ptr 1
		.amdhsa_user_sgpr_dispatch_id 0
		.amdhsa_user_sgpr_kernarg_preload_length 0
		.amdhsa_user_sgpr_kernarg_preload_offset 0
		.amdhsa_user_sgpr_private_segment_size 0
		.amdhsa_uses_dynamic_stack 0
		.amdhsa_enable_private_segment 0
		.amdhsa_system_sgpr_workgroup_id_x 1
		.amdhsa_system_sgpr_workgroup_id_y 0
		.amdhsa_system_sgpr_workgroup_id_z 0
		.amdhsa_system_sgpr_workgroup_info 0
		.amdhsa_system_vgpr_workitem_id 2
		.amdhsa_next_free_vgpr 238
		.amdhsa_next_free_sgpr 98
		.amdhsa_accum_offset 240
		.amdhsa_reserve_vcc 1
		.amdhsa_float_round_mode_32 0
		.amdhsa_float_round_mode_16_64 0
		.amdhsa_float_denorm_mode_32 3
		.amdhsa_float_denorm_mode_16_64 3
		.amdhsa_dx10_clamp 1
		.amdhsa_ieee_mode 1
		.amdhsa_fp16_overflow 0
		.amdhsa_tg_split 0
		.amdhsa_exception_fp_ieee_invalid_op 0
		.amdhsa_exception_fp_denorm_src 0
		.amdhsa_exception_fp_ieee_div_zero 0
		.amdhsa_exception_fp_ieee_overflow 0
		.amdhsa_exception_fp_ieee_underflow 0
		.amdhsa_exception_fp_ieee_inexact 0
		.amdhsa_exception_int_div_zero 0
	.end_amdhsa_kernel

amdhsa.kernels:
  - .agpr_count:     0
    .args:
      - .offset:         0
        .size:           248
        .value_kind:     by_value
      - .offset:         248
        .size:           4
        .value_kind:     by_value
      - .offset:         252
        .size:           4
        .value_kind:     by_value
      - .offset:         256
        .size:           4
        .value_kind:     hidden_block_count_x
      - .offset:         260
        .size:           4
        .value_kind:     hidden_block_count_y
      - .offset:         264
        .size:           4
        .value_kind:     hidden_block_count_z
      - .offset:         268
        .size:           2
        .value_kind:     hidden_group_size_x
      - .offset:         270
        .size:           2
        .value_kind:     hidden_group_size_y
      - .offset:         272
        .size:           2
        .value_kind:     hidden_group_size_z
      - .offset:         274
        .size:           2
        .value_kind:     hidden_remainder_x
      - .offset:         276
        .size:           2
        .value_kind:     hidden_remainder_y
      - .offset:         278
        .size:           2
        .value_kind:     hidden_remainder_z
      - .offset:         296
        .size:           8
        .value_kind:     hidden_global_offset_x
      - .offset:         304
        .size:           8
        .value_kind:     hidden_global_offset_y
      - .offset:         312
        .size:           8
        .value_kind:     hidden_global_offset_z
      - .offset:         320
        .size:           2
        .value_kind:     hidden_grid_dims
      - .offset:         344
        .size:           8
        .value_kind:     hidden_multigrid_sync_arg
    .group_segment_fixed_size: 73744
    .kernarg_segment_align: 8
    .kernarg_segment_size: 512
    .language:       OpenCL C
    .language_version:
      - 2
      - 0
    .max_flat_workgroup_size: 256
    .name:           _Z15yoco_megakernel5KArgsii
    .private_segment_fixed_size: 0
    .sgpr_count:     104
    .sgpr_spill_count: 38
    .symbol:         _Z15yoco_megakernel5KArgsii.kd
    .uniform_work_group_size: 1
    .uses_dynamic_stack: false
    .vgpr_count:     238
    .vgpr_spill_count: 0
    .wavefront_size: 64
